# KIND0 loop: first two PV MFMAs of the previous tile moved right behind the barrier to cover the K-fragment LDS read latency before the QK MFMAs
# speedup vs baseline: 1.0040x; 1.0032x over previous
; #define MFMA(a, b, c) __builtin_amdgcn_mfma_f32_32x32x16_bf16((a), (b), (c), 0, 0, 0)
; #define LOAD_VF() do { \
;             __builtin_amdgcn_sched_barrier(0); \
;             _Pragma("unroll") for (int s = 0; s < 4; ++s) \
;                 _Pragma("unroll") for (int dt = 0; dt < 2; ++dt) vf[2 * s + dt] = ldv_frag(sv, 32 * dt + r, 2 * s + h, xr); \
;             __builtin_amdgcn_sched_barrier(0); } while (0)
; DI void softmax_tile(f32x16 (&S)[2], float& lsum) {
;     f2_t ps = {0.f, 0.f};
; #pragma unroll
;     for (int t = 0; t < 2; ++t)
; #pragma unroll
;         for (int e = 0; e < 16; e += 2) {
;             f2_t pv; pv.x = __builtin_amdgcn_exp2f(S[t][e]); pv.y = __builtin_amdgcn_exp2f(S[t][e + 1]);
;             S[t][e] = pv.x; S[t][e + 1] = pv.y;
;             ps += pv;
;         }
;     lsum += ps.x + ps.y;
; }
; DI void pv_tile(const f32x16 (&S)[2], f32x16 (&O)[2], const bf16x8 (&vf)[8]) {
; #pragma unroll
;     for (int s = 0; s < 4; ++s) {
;         const bf16x8 pf = pack8(S[s >> 1], s & 1);
; #pragma unroll
;         for (int dt = 0; dt < 2; ++dt) O[dt] = MFMA(vf[2 * s + dt], pf, O[dt]);
;     }
; }
; template <int KIND>
; DI void attn_unit(const Params& p, int l, int b, int head, int qt, int qcol, int kcol, int vfeat, int gcol, int mixcol,
;                   int t1, int n1, int t2, int n2, char* smem) {
;     ...
;             if (KIND == 0) {
;                 f32x16 S0[2], S1[2];
; #pragma unroll
;                 for (int t = 0; t < 2; ++t) { S0[t] = MFMA(kf[t], qf[0], cz); S1[t] = MFMA(kf[4 + t], qf[2], cz); }
; #pragma unroll
;                 for (int t = 0; t < 2; ++t) { S0[t] = MFMA(kf[2 + t], qf[1], S0[t]); S1[t] = MFMA(kf[6 + t], qf[3], S1[t]); }
;                 LOAD_VF();
;                 softmax_tile(S0, l0);
;                 pv_tile(S0, O0, vf);
;                 softmax_tile(S1, l1);
;                 pv_tile(S1, O1, vf);
.LBB0_82:
	s_waitcnt vmcnt(4)
	s_barrier
	ds_read_b128 v[234:237], v225
	ds_read_b128 v[238:241], v225 offset:4096
	ds_read_b128 v[242:245], v222
	ds_read_b128 v[246:249], v222 offset:4096
	s_lshl_b32 s101, s34, 14
	s_add_i32 s101, s101, s100
	s_add_i32 s42, s35, 1
	s_cmp_lg_u32 s35, 2
	s_cselect_b32 s35, s42, 0
	s_add_i32 s42, s34, 1
	v_mfma_f32_32x32x16_bf16 v[64:79], v[188:191], v[96:99], v[64:79]
	v_add_f32_e32 v252, v80, v252
	v_add_f32_e32 v253, v81, v253
	v_cvt_pk_bf16_f32 v80, v80, v81
	v_add_f32_e32 v252, v82, v252
	v_add_f32_e32 v253, v83, v253
	v_cvt_pk_bf16_f32 v81, v82, v83
	v_mfma_f32_32x32x16_bf16 v[16:31], v[184:187], v[96:99], v[16:31]
	v_add_f32_e32 v252, v84, v252
	v_add_f32_e32 v253, v85, v253
	v_cvt_pk_bf16_f32 v82, v84, v85
	v_add_f32_e32 v252, v86, v252
	v_add_f32_e32 v253, v87, v253
	v_cvt_pk_bf16_f32 v83, v86, v87
	s_mov_b32 m0, s101
	s_waitcnt lgkmcnt(0)
	v_mfma_f32_32x32x16_bf16 v[128:143], v[234:237], v[152:155], v[0:15]
	global_load_lds_dwordx4 v226, s[62:63]
	s_add_u32 m0, s101, 0x1000
	v_add_f32_e32 v252, v88, v252
	v_add_f32_e32 v253, v89, v253
	v_cvt_pk_bf16_f32 v88, v88, v89
	v_mfma_f32_32x32x16_bf16 v[112:127], v[238:241], v[152:155], v[0:15]
	global_load_lds_dwordx4 v227, s[62:63]
	s_add_u32 m0, s101, 0x2000
	v_add_f32_e32 v252, v90, v252
	v_add_f32_e32 v253, v91, v253
	v_cvt_pk_bf16_f32 v89, v90, v91
	v_mfma_f32_32x32x16_bf16 v[128:143], v[242:245], v[144:147], v[128:143]
	global_load_lds_dwordx4 v226, s[98:99]
	s_add_u32 m0, s101, 0x3000
	v_add_f32_e32 v252, v92, v252
	v_add_f32_e32 v253, v93, v253
	v_cvt_pk_bf16_f32 v90, v92, v93
	v_mfma_f32_32x32x16_bf16 v[112:127], v[246:249], v[144:147], v[112:127]
	global_load_lds_dwordx4 v227, s[98:99]
	v_add_f32_e32 v252, v94, v252
	v_add_f32_e32 v253, v95, v253
	v_cvt_pk_bf16_f32 v91, v94, v95
	v_add_f32_e32 v252, v252, v253
	v_add_f32_e32 v194, v194, v252
	s_cmp_lg_u32 s34, 2
	s_cselect_b32 s34, s42, 0
	s_add_u32 s62, s62, 0x2000
	s_addc_u32 s63, s63, 0
	s_add_u32 s98, s98, 0x2000
	s_addc_u32 s99, s99, 0
	ds_read_b128 v[234:237], v223
	ds_read_b128 v[238:241], v223 offset:4096
	ds_read_b128 v[242:245], v224
	ds_read_b128 v[246:249], v224 offset:4096
	v_mfma_f32_32x32x16_bf16 v[64:79], v[180:183], v[104:107], v[64:79]
	v_exp_f32_e32 v128, v128
	v_exp_f32_e32 v129, v129
	v_exp_f32_e32 v130, v130
	v_exp_f32_e32 v131, v131
	v_exp_f32_e32 v132, v132
	v_exp_f32_e32 v133, v133
	v_mfma_f32_32x32x16_bf16 v[16:31], v[176:179], v[104:107], v[16:31]
	v_exp_f32_e32 v134, v134
	v_exp_f32_e32 v135, v135
	v_exp_f32_e32 v136, v136
	v_exp_f32_e32 v137, v137
	v_exp_f32_e32 v138, v138
	v_exp_f32_e32 v139, v139
	v_add_f32_e64 v250, v128, 0
	v_add_f32_e64 v251, v129, 0
	v_cvt_pk_bf16_f32 v128, v128, v129
	v_add_f32_e32 v250, v130, v250
	v_add_f32_e32 v251, v131, v251
	v_cvt_pk_bf16_f32 v129, v130, v131
	v_add_f32_e32 v250, v132, v250
	v_add_f32_e32 v251, v133, v251
	v_cvt_pk_bf16_f32 v130, v132, v133
	v_mfma_f32_32x32x16_bf16 v[64:79], v[172:175], v[80:83], v[64:79]
	v_exp_f32_e32 v140, v140
	v_exp_f32_e32 v141, v141
	v_exp_f32_e32 v142, v142
	v_exp_f32_e32 v143, v143
	v_exp_f32_e32 v112, v112
	v_add_f32_e32 v250, v134, v250
	v_add_f32_e32 v251, v135, v251
	v_cvt_pk_bf16_f32 v131, v134, v135
	v_add_f32_e32 v250, v136, v250
	v_add_f32_e32 v251, v137, v251
	v_cvt_pk_bf16_f32 v136, v136, v137
	v_add_f32_e32 v250, v138, v250
	v_add_f32_e32 v251, v139, v251
	v_cvt_pk_bf16_f32 v137, v138, v139
	v_mfma_f32_32x32x16_bf16 v[16:31], v[168:171], v[80:83], v[16:31]
	v_exp_f32_e32 v113, v113
	v_exp_f32_e32 v114, v114
	v_exp_f32_e32 v115, v115
	v_exp_f32_e32 v116, v116
	v_exp_f32_e32 v117, v117
	v_add_f32_e32 v250, v140, v250
	v_add_f32_e32 v251, v141, v251
	v_cvt_pk_bf16_f32 v138, v140, v141
	v_add_f32_e32 v250, v142, v250
	v_add_f32_e32 v251, v143, v251
	v_cvt_pk_bf16_f32 v139, v142, v143
	v_mfma_f32_32x32x16_bf16 v[64:79], v[164:167], v[88:91], v[64:79]
	v_exp_f32_e32 v118, v118
	v_exp_f32_e32 v119, v119
	v_exp_f32_e32 v120, v120
	v_exp_f32_e32 v121, v121
	v_exp_f32_e32 v122, v122
	v_mfma_f32_32x32x16_bf16 v[16:31], v[160:163], v[88:91], v[16:31]
	v_exp_f32_e32 v123, v123
	v_exp_f32_e32 v124, v124
	v_exp_f32_e32 v125, v125
	v_exp_f32_e32 v126, v126
	v_exp_f32_e32 v127, v127
	s_waitcnt lgkmcnt(0)
	ds_read_b128 v[188:191], v225 offset:8192
	ds_read_b128 v[184:187], v225 offset:12288
	ds_read_b128 v[180:183], v222 offset:8192
	ds_read_b128 v[176:179], v222 offset:12288
	ds_read_b128 v[172:175], v223 offset:8192
	ds_read_b128 v[168:171], v223 offset:12288
	ds_read_b128 v[164:167], v224 offset:8192
	ds_read_b128 v[160:163], v224 offset:12288
	v_mfma_f32_32x32x16_bf16 v[96:111], v[234:237], v[156:159], v[0:15]
	v_add_f32_e32 v250, v112, v250
	v_add_f32_e32 v251, v113, v251
	v_cvt_pk_bf16_f32 v112, v112, v113
	v_add_f32_e32 v250, v114, v250
	v_add_f32_e32 v251, v115, v251
	v_cvt_pk_bf16_f32 v113, v114, v115
	v_mfma_f32_32x32x16_bf16 v[80:95], v[238:241], v[156:159], v[0:15]
	v_add_f32_e32 v250, v116, v250
	v_add_f32_e32 v251, v117, v251
	v_cvt_pk_bf16_f32 v114, v116, v117
	v_add_f32_e32 v250, v118, v250
	v_add_f32_e32 v251, v119, v251
	v_cvt_pk_bf16_f32 v115, v118, v119
	v_mfma_f32_32x32x16_bf16 v[96:111], v[242:245], v[148:151], v[96:111]
	v_add_f32_e32 v250, v120, v250
	v_add_f32_e32 v251, v121, v251
	v_cvt_pk_bf16_f32 v120, v120, v121
	v_add_f32_e32 v250, v122, v250
	v_add_f32_e32 v251, v123, v251
	v_cvt_pk_bf16_f32 v121, v122, v123
	v_mfma_f32_32x32x16_bf16 v[80:95], v[246:249], v[148:151], v[80:95]
	v_add_f32_e32 v250, v124, v250
	v_add_f32_e32 v251, v125, v251
	v_cvt_pk_bf16_f32 v122, v124, v125
	v_add_f32_e32 v250, v126, v250
	v_add_f32_e32 v251, v127, v251
	v_cvt_pk_bf16_f32 v123, v126, v127
	v_add_f32_e32 v250, v250, v251
	v_add_f32_e32 v195, v195, v250
	s_add_u32 s4, s4, 0x2000
	s_addc_u32 s5, s5, 0
	s_waitcnt lgkmcnt(0)
; #define MFMA(a, b, c) __builtin_amdgcn_mfma_f32_32x32x16_bf16((a), (b), (c), 0, 0, 0)
; #define LOAD_VF() do { \
;             __builtin_amdgcn_sched_barrier(0); \
;             _Pragma("unroll") for (int s = 0; s < 4; ++s) \
;                 _Pragma("unroll") for (int dt = 0; dt < 2; ++dt) vf[2 * s + dt] = ldv_frag(sv, 32 * dt + r, 2 * s + h, xr); \
;             __builtin_amdgcn_sched_barrier(0); } while (0)
; DI void softmax_tile(f32x16 (&S)[2], float& lsum) {
;     f2_t ps = {0.f, 0.f};
; #pragma unroll
;     for (int t = 0; t < 2; ++t)
; #pragma unroll
;         for (int e = 0; e < 16; e += 2) {
;             f2_t pv; pv.x = __builtin_amdgcn_exp2f(S[t][e]); pv.y = __builtin_amdgcn_exp2f(S[t][e + 1]);
;             S[t][e] = pv.x; S[t][e + 1] = pv.y;
;             ps += pv;
;         }
;     lsum += ps.x + ps.y;
; }
; DI void pv_tile(const f32x16 (&S)[2], f32x16 (&O)[2], const bf16x8 (&vf)[8]) {
; #pragma unroll
;     for (int s = 0; s < 4; ++s) {
;         const bf16x8 pf = pack8(S[s >> 1], s & 1);
; #pragma unroll
;         for (int dt = 0; dt < 2; ++dt) O[dt] = MFMA(vf[2 * s + dt], pf, O[dt]);
;     }
; }
; template <int KIND>
; DI void attn_unit(const Params& p, int l, int b, int head, int qt, int qcol, int kcol, int vfeat, int gcol, int mixcol,
;                   int t1, int n1, int t2, int n2, char* smem) {
;     ...
;             if (KIND == 0) {
;                 f32x16 S0[2], S1[2];
; #pragma unroll
;                 for (int t = 0; t < 2; ++t) { S0[t] = MFMA(kf[t], qf[0], cz); S1[t] = MFMA(kf[4 + t], qf[2], cz); }
; #pragma unroll
;                 for (int t = 0; t < 2; ++t) { S0[t] = MFMA(kf[2 + t], qf[1], S0[t]); S1[t] = MFMA(kf[6 + t], qf[3], S1[t]); }
;                 LOAD_VF();
;                 softmax_tile(S0, l0);
;                 pv_tile(S0, O0, vf);
;                 softmax_tile(S1, l1);
;                 pv_tile(S1, O1, vf);
	v_mfma_f32_32x32x16_bf16 v[48:63], v[188:191], v[128:131], v[48:63]
	v_exp_f32_e32 v96, v96
	v_exp_f32_e32 v97, v97
	v_exp_f32_e32 v98, v98
	v_exp_f32_e32 v99, v99
	v_mfma_f32_32x32x16_bf16 v[32:47], v[184:187], v[128:131], v[32:47]
	v_exp_f32_e32 v100, v100
	v_exp_f32_e32 v101, v101
	v_exp_f32_e32 v102, v102
	v_exp_f32_e32 v103, v103
	v_mfma_f32_32x32x16_bf16 v[48:63], v[180:183], v[136:139], v[48:63]
	v_exp_f32_e32 v104, v104
	v_exp_f32_e32 v105, v105
	v_exp_f32_e32 v106, v106
	v_exp_f32_e32 v107, v107
	v_add_f32_e64 v252, v96, 0
	v_add_f32_e64 v253, v97, 0
	v_cvt_pk_bf16_f32 v96, v96, v97
	v_add_f32_e32 v252, v98, v252
	v_add_f32_e32 v253, v99, v253
	v_cvt_pk_bf16_f32 v97, v98, v99
	v_mfma_f32_32x32x16_bf16 v[32:47], v[176:179], v[136:139], v[32:47]
	v_exp_f32_e32 v108, v108
	v_exp_f32_e32 v109, v109
	v_exp_f32_e32 v110, v110
	v_exp_f32_e32 v111, v111
	v_add_f32_e32 v252, v100, v252
	v_add_f32_e32 v253, v101, v253
	v_cvt_pk_bf16_f32 v98, v100, v101
	v_add_f32_e32 v252, v102, v252
	v_add_f32_e32 v253, v103, v253
	v_cvt_pk_bf16_f32 v99, v102, v103
	v_mfma_f32_32x32x16_bf16 v[48:63], v[172:175], v[112:115], v[48:63]
	v_exp_f32_e32 v80, v80
	v_exp_f32_e32 v81, v81
	v_exp_f32_e32 v82, v82
	v_exp_f32_e32 v83, v83
	v_add_f32_e32 v252, v104, v252
	v_add_f32_e32 v253, v105, v253
	v_cvt_pk_bf16_f32 v104, v104, v105
	v_add_f32_e32 v252, v106, v252
	v_add_f32_e32 v253, v107, v253
	v_cvt_pk_bf16_f32 v105, v106, v107
	v_mfma_f32_32x32x16_bf16 v[32:47], v[168:171], v[112:115], v[32:47]
	v_exp_f32_e32 v84, v84
	v_exp_f32_e32 v85, v85
	v_exp_f32_e32 v86, v86
	v_exp_f32_e32 v87, v87
	v_add_f32_e32 v252, v108, v252
	v_add_f32_e32 v253, v109, v253
	v_cvt_pk_bf16_f32 v106, v108, v109
	v_add_f32_e32 v252, v110, v252
	v_add_f32_e32 v253, v111, v253
	v_cvt_pk_bf16_f32 v107, v110, v111
	v_mfma_f32_32x32x16_bf16 v[48:63], v[164:167], v[120:123], v[48:63]
	v_exp_f32_e32 v88, v88
	v_exp_f32_e32 v89, v89
	v_exp_f32_e32 v90, v90
	v_exp_f32_e32 v91, v91
	v_mfma_f32_32x32x16_bf16 v[32:47], v[160:163], v[120:123], v[32:47]
	v_exp_f32_e32 v92, v92
	v_exp_f32_e32 v93, v93
	v_exp_f32_e32 v94, v94
	v_exp_f32_e32 v95, v95
	s_cmp_eq_u32 s52, s4
	s_cbranch_scc1 .Lk0u_exit
	s_waitcnt vmcnt(4)
	s_barrier
	ds_read_b128 v[234:237], v196
	ds_read_b128 v[238:241], v196 offset:4096
	ds_read_b128 v[242:245], v197
	ds_read_b128 v[246:249], v197 offset:4096
	s_lshl_b32 s101, s34, 14
	s_add_i32 s101, s101, s100
	s_add_i32 s42, s35, 1
	s_cmp_lg_u32 s35, 2
	s_cselect_b32 s35, s42, 0
	s_add_i32 s42, s34, 1
	v_mfma_f32_32x32x16_bf16 v[64:79], v[188:191], v[96:99], v[64:79]
	v_add_f32_e32 v252, v80, v252
	v_add_f32_e32 v253, v81, v253
	v_cvt_pk_bf16_f32 v80, v80, v81
	v_add_f32_e32 v252, v82, v252
	v_add_f32_e32 v253, v83, v253
	v_cvt_pk_bf16_f32 v81, v82, v83
	v_mfma_f32_32x32x16_bf16 v[16:31], v[184:187], v[96:99], v[16:31]
	v_add_f32_e32 v252, v84, v252
	v_add_f32_e32 v253, v85, v253
	v_cvt_pk_bf16_f32 v82, v84, v85
	v_add_f32_e32 v252, v86, v252
	v_add_f32_e32 v253, v87, v253
	v_cvt_pk_bf16_f32 v83, v86, v87
	s_mov_b32 m0, s101
	s_waitcnt lgkmcnt(0)
	v_mfma_f32_32x32x16_bf16 v[128:143], v[234:237], v[152:155], v[0:15]
	global_load_lds_dwordx4 v226, s[62:63]
	s_add_u32 m0, s101, 0x1000
	v_add_f32_e32 v252, v88, v252
	v_add_f32_e32 v253, v89, v253
	v_cvt_pk_bf16_f32 v88, v88, v89
	v_mfma_f32_32x32x16_bf16 v[112:127], v[238:241], v[152:155], v[0:15]
	global_load_lds_dwordx4 v227, s[62:63]
	s_add_u32 m0, s101, 0x2000
	v_add_f32_e32 v252, v90, v252
	v_add_f32_e32 v253, v91, v253
	v_cvt_pk_bf16_f32 v89, v90, v91
	v_mfma_f32_32x32x16_bf16 v[128:143], v[242:245], v[144:147], v[128:143]
	global_load_lds_dwordx4 v226, s[98:99]
	s_add_u32 m0, s101, 0x3000
	v_add_f32_e32 v252, v92, v252
	v_add_f32_e32 v253, v93, v253
	v_cvt_pk_bf16_f32 v90, v92, v93
	v_mfma_f32_32x32x16_bf16 v[112:127], v[246:249], v[144:147], v[112:127]
	global_load_lds_dwordx4 v227, s[98:99]
	v_add_f32_e32 v252, v94, v252
	v_add_f32_e32 v253, v95, v253
	v_cvt_pk_bf16_f32 v91, v94, v95
	v_add_f32_e32 v252, v252, v253
	v_add_f32_e32 v194, v194, v252
	s_cmp_lg_u32 s34, 2
	s_cselect_b32 s34, s42, 0
	s_add_u32 s62, s62, 0x2000
	s_addc_u32 s63, s63, 0
	s_add_u32 s98, s98, 0x2000
	s_addc_u32 s99, s99, 0
	ds_read_b128 v[234:237], v198
	ds_read_b128 v[238:241], v198 offset:4096
	ds_read_b128 v[242:245], v199
	ds_read_b128 v[246:249], v199 offset:4096
	v_mfma_f32_32x32x16_bf16 v[64:79], v[180:183], v[104:107], v[64:79]
	v_exp_f32_e32 v128, v128
	v_exp_f32_e32 v129, v129
	v_exp_f32_e32 v130, v130
	v_exp_f32_e32 v131, v131
	v_exp_f32_e32 v132, v132
	v_exp_f32_e32 v133, v133
	v_mfma_f32_32x32x16_bf16 v[16:31], v[176:179], v[104:107], v[16:31]
	v_exp_f32_e32 v134, v134
	v_exp_f32_e32 v135, v135
	v_exp_f32_e32 v136, v136
	v_exp_f32_e32 v137, v137
	v_exp_f32_e32 v138, v138
	v_exp_f32_e32 v139, v139
	v_add_f32_e64 v250, v128, 0
	v_add_f32_e64 v251, v129, 0
	v_cvt_pk_bf16_f32 v128, v128, v129
	v_add_f32_e32 v250, v130, v250
	v_add_f32_e32 v251, v131, v251
	v_cvt_pk_bf16_f32 v129, v130, v131
	v_add_f32_e32 v250, v132, v250
	v_add_f32_e32 v251, v133, v251
	v_cvt_pk_bf16_f32 v130, v132, v133
	v_mfma_f32_32x32x16_bf16 v[64:79], v[172:175], v[80:83], v[64:79]
	v_exp_f32_e32 v140, v140
	v_exp_f32_e32 v141, v141
	v_exp_f32_e32 v142, v142
	v_exp_f32_e32 v143, v143
	v_exp_f32_e32 v112, v112
	v_add_f32_e32 v250, v134, v250
	v_add_f32_e32 v251, v135, v251
	v_cvt_pk_bf16_f32 v131, v134, v135
	v_add_f32_e32 v250, v136, v250
	v_add_f32_e32 v251, v137, v251
	v_cvt_pk_bf16_f32 v136, v136, v137
	v_add_f32_e32 v250, v138, v250
	v_add_f32_e32 v251, v139, v251
	v_cvt_pk_bf16_f32 v137, v138, v139
	v_mfma_f32_32x32x16_bf16 v[16:31], v[168:171], v[80:83], v[16:31]
	v_exp_f32_e32 v113, v113
	v_exp_f32_e32 v114, v114
	v_exp_f32_e32 v115, v115
	v_exp_f32_e32 v116, v116
	v_exp_f32_e32 v117, v117
	v_add_f32_e32 v250, v140, v250
	v_add_f32_e32 v251, v141, v251
	v_cvt_pk_bf16_f32 v138, v140, v141
	v_add_f32_e32 v250, v142, v250
	v_add_f32_e32 v251, v143, v251
	v_cvt_pk_bf16_f32 v139, v142, v143
	v_mfma_f32_32x32x16_bf16 v[64:79], v[164:167], v[88:91], v[64:79]
	v_exp_f32_e32 v118, v118
	v_exp_f32_e32 v119, v119
	v_exp_f32_e32 v120, v120
	v_exp_f32_e32 v121, v121
	v_exp_f32_e32 v122, v122
	v_mfma_f32_32x32x16_bf16 v[16:31], v[160:163], v[88:91], v[16:31]
	v_exp_f32_e32 v123, v123
	v_exp_f32_e32 v124, v124
	v_exp_f32_e32 v125, v125
	v_exp_f32_e32 v126, v126
	v_exp_f32_e32 v127, v127
	s_waitcnt lgkmcnt(0)
; #define MFMA(a, b, c) __builtin_amdgcn_mfma_f32_32x32x16_bf16((a), (b), (c), 0, 0, 0)
; #define LOAD_VF() do { \
;             __builtin_amdgcn_sched_barrier(0); \
;             _Pragma("unroll") for (int s = 0; s < 4; ++s) \
;                 _Pragma("unroll") for (int dt = 0; dt < 2; ++dt) vf[2 * s + dt] = ldv_frag(sv, 32 * dt + r, 2 * s + h, xr); \
;             __builtin_amdgcn_sched_barrier(0); } while (0)
; DI void softmax_tile(f32x16 (&S)[2], float& lsum) {
;     f2_t ps = {0.f, 0.f};
; #pragma unroll
;     for (int t = 0; t < 2; ++t)
; #pragma unroll
;         for (int e = 0; e < 16; e += 2) {
;             f2_t pv; pv.x = __builtin_amdgcn_exp2f(S[t][e]); pv.y = __builtin_amdgcn_exp2f(S[t][e + 1]);
;             S[t][e] = pv.x; S[t][e + 1] = pv.y;
;             ps += pv;
;         }
;     lsum += ps.x + ps.y;
; }
; DI void pv_tile(const f32x16 (&S)[2], f32x16 (&O)[2], const bf16x8 (&vf)[8]) {
; #pragma unroll
;     for (int s = 0; s < 4; ++s) {
;         const bf16x8 pf = pack8(S[s >> 1], s & 1);
; #pragma unroll
;         for (int dt = 0; dt < 2; ++dt) O[dt] = MFMA(vf[2 * s + dt], pf, O[dt]);
;     }
; }
; template <int KIND>
; DI void attn_unit(const Params& p, int l, int b, int head, int qt, int qcol, int kcol, int vfeat, int gcol, int mixcol,
;                   int t1, int n1, int t2, int n2, char* smem) {
;     ...
;             if (KIND == 0) {
;                 f32x16 S0[2], S1[2];
; #pragma unroll
;                 for (int t = 0; t < 2; ++t) { S0[t] = MFMA(kf[t], qf[0], cz); S1[t] = MFMA(kf[4 + t], qf[2], cz); }
; #pragma unroll
;                 for (int t = 0; t < 2; ++t) { S0[t] = MFMA(kf[2 + t], qf[1], S0[t]); S1[t] = MFMA(kf[6 + t], qf[3], S1[t]); }
;                 LOAD_VF();
;                 softmax_tile(S0, l0);
;                 pv_tile(S0, O0, vf);
;                 softmax_tile(S1, l1);
;                 pv_tile(S1, O1, vf);
	ds_read_b128 v[188:191], v196 offset:8192
	ds_read_b128 v[184:187], v196 offset:12288
	ds_read_b128 v[180:183], v197 offset:8192
	ds_read_b128 v[176:179], v197 offset:12288
	ds_read_b128 v[172:175], v198 offset:8192
	ds_read_b128 v[168:171], v198 offset:12288
	ds_read_b128 v[164:167], v199 offset:8192
	ds_read_b128 v[160:163], v199 offset:12288
	v_mfma_f32_32x32x16_bf16 v[96:111], v[234:237], v[156:159], v[0:15]
	v_add_f32_e32 v250, v112, v250
	v_add_f32_e32 v251, v113, v251
	v_cvt_pk_bf16_f32 v112, v112, v113
	v_add_f32_e32 v250, v114, v250
	v_add_f32_e32 v251, v115, v251
	v_cvt_pk_bf16_f32 v113, v114, v115
	v_mfma_f32_32x32x16_bf16 v[80:95], v[238:241], v[156:159], v[0:15]
	v_add_f32_e32 v250, v116, v250
	v_add_f32_e32 v251, v117, v251
	v_cvt_pk_bf16_f32 v114, v116, v117
	v_add_f32_e32 v250, v118, v250
	v_add_f32_e32 v251, v119, v251
	v_cvt_pk_bf16_f32 v115, v118, v119
	v_mfma_f32_32x32x16_bf16 v[96:111], v[242:245], v[148:151], v[96:111]
	v_add_f32_e32 v250, v120, v250
	v_add_f32_e32 v251, v121, v251
	v_cvt_pk_bf16_f32 v120, v120, v121
	v_add_f32_e32 v250, v122, v250
	v_add_f32_e32 v251, v123, v251
	v_cvt_pk_bf16_f32 v121, v122, v123
	v_mfma_f32_32x32x16_bf16 v[80:95], v[246:249], v[148:151], v[80:95]
	v_add_f32_e32 v250, v124, v250
	v_add_f32_e32 v251, v125, v251
	v_cvt_pk_bf16_f32 v122, v124, v125
	v_add_f32_e32 v250, v126, v250
	v_add_f32_e32 v251, v127, v251
	v_cvt_pk_bf16_f32 v123, v126, v127
	v_add_f32_e32 v250, v250, v251
	v_add_f32_e32 v195, v195, v250
	s_add_u32 s4, s4, 0x2000
	s_addc_u32 s5, s5, 0
	s_waitcnt lgkmcnt(0)
	v_mfma_f32_32x32x16_bf16 v[48:63], v[188:191], v[128:131], v[48:63]
	v_exp_f32_e32 v96, v96
	v_exp_f32_e32 v97, v97
	v_exp_f32_e32 v98, v98
	v_exp_f32_e32 v99, v99
	v_mfma_f32_32x32x16_bf16 v[32:47], v[184:187], v[128:131], v[32:47]
	v_exp_f32_e32 v100, v100
	v_exp_f32_e32 v101, v101
	v_exp_f32_e32 v102, v102
	v_exp_f32_e32 v103, v103
	v_mfma_f32_32x32x16_bf16 v[48:63], v[180:183], v[136:139], v[48:63]
	v_exp_f32_e32 v104, v104
	v_exp_f32_e32 v105, v105
	v_exp_f32_e32 v106, v106
	v_exp_f32_e32 v107, v107
	v_add_f32_e64 v252, v96, 0
	v_add_f32_e64 v253, v97, 0
	v_cvt_pk_bf16_f32 v96, v96, v97
	v_add_f32_e32 v252, v98, v252
	v_add_f32_e32 v253, v99, v253
	v_cvt_pk_bf16_f32 v97, v98, v99
	v_mfma_f32_32x32x16_bf16 v[32:47], v[176:179], v[136:139], v[32:47]
	v_exp_f32_e32 v108, v108
	v_exp_f32_e32 v109, v109
	v_exp_f32_e32 v110, v110
	v_exp_f32_e32 v111, v111
	v_add_f32_e32 v252, v100, v252
	v_add_f32_e32 v253, v101, v253
	v_cvt_pk_bf16_f32 v98, v100, v101
	v_add_f32_e32 v252, v102, v252
	v_add_f32_e32 v253, v103, v253
	v_cvt_pk_bf16_f32 v99, v102, v103
	v_mfma_f32_32x32x16_bf16 v[48:63], v[172:175], v[112:115], v[48:63]
	v_exp_f32_e32 v80, v80
	v_exp_f32_e32 v81, v81
	v_exp_f32_e32 v82, v82
	v_exp_f32_e32 v83, v83
	v_add_f32_e32 v252, v104, v252
	v_add_f32_e32 v253, v105, v253
	v_cvt_pk_bf16_f32 v104, v104, v105
	v_add_f32_e32 v252, v106, v252
	v_add_f32_e32 v253, v107, v253
	v_cvt_pk_bf16_f32 v105, v106, v107
	v_mfma_f32_32x32x16_bf16 v[32:47], v[168:171], v[112:115], v[32:47]
	v_exp_f32_e32 v84, v84
	v_exp_f32_e32 v85, v85
	v_exp_f32_e32 v86, v86
	v_exp_f32_e32 v87, v87
	v_add_f32_e32 v252, v108, v252
	v_add_f32_e32 v253, v109, v253
	v_cvt_pk_bf16_f32 v106, v108, v109
	v_add_f32_e32 v252, v110, v252
	v_add_f32_e32 v253, v111, v253
	v_cvt_pk_bf16_f32 v107, v110, v111
	v_mfma_f32_32x32x16_bf16 v[48:63], v[164:167], v[120:123], v[48:63]
	v_exp_f32_e32 v88, v88
	v_exp_f32_e32 v89, v89
	v_exp_f32_e32 v90, v90
	v_exp_f32_e32 v91, v91
	v_mfma_f32_32x32x16_bf16 v[32:47], v[160:163], v[120:123], v[32:47]
	v_exp_f32_e32 v92, v92
	v_exp_f32_e32 v93, v93
	v_exp_f32_e32 v94, v94
	v_exp_f32_e32 v95, v95
	s_cmp_eq_u32 s52, s4
	s_cbranch_scc1 .Lk0u_exit
	s_waitcnt vmcnt(4)
	s_barrier
	ds_read_b128 v[234:237], v228
	ds_read_b128 v[238:241], v228 offset:4096
	ds_read_b128 v[242:245], v229
	ds_read_b128 v[246:249], v229 offset:4096
	s_lshl_b32 s101, s34, 14
	s_add_i32 s101, s101, s100
	s_add_i32 s42, s35, 1
	s_cmp_lg_u32 s35, 2
	s_cselect_b32 s35, s42, 0
	s_add_i32 s42, s34, 1
	v_mfma_f32_32x32x16_bf16 v[64:79], v[188:191], v[96:99], v[64:79]
	v_add_f32_e32 v252, v80, v252
	v_add_f32_e32 v253, v81, v253
	v_cvt_pk_bf16_f32 v80, v80, v81
	v_add_f32_e32 v252, v82, v252
	v_add_f32_e32 v253, v83, v253
	v_cvt_pk_bf16_f32 v81, v82, v83
	v_mfma_f32_32x32x16_bf16 v[16:31], v[184:187], v[96:99], v[16:31]
	v_add_f32_e32 v252, v84, v252
	v_add_f32_e32 v253, v85, v253
	v_cvt_pk_bf16_f32 v82, v84, v85
	v_add_f32_e32 v252, v86, v252
	v_add_f32_e32 v253, v87, v253
	v_cvt_pk_bf16_f32 v83, v86, v87
	s_mov_b32 m0, s101
	s_waitcnt lgkmcnt(0)
; #define MFMA(a, b, c) __builtin_amdgcn_mfma_f32_32x32x16_bf16((a), (b), (c), 0, 0, 0)
; #define LOAD_VF() do { \
;             __builtin_amdgcn_sched_barrier(0); \
;             _Pragma("unroll") for (int s = 0; s < 4; ++s) \
;                 _Pragma("unroll") for (int dt = 0; dt < 2; ++dt) vf[2 * s + dt] = ldv_frag(sv, 32 * dt + r, 2 * s + h, xr); \
;             __builtin_amdgcn_sched_barrier(0); } while (0)
; DI void softmax_tile(f32x16 (&S)[2], float& lsum) {
;     f2_t ps = {0.f, 0.f};
; #pragma unroll
;     for (int t = 0; t < 2; ++t)
; #pragma unroll
;         for (int e = 0; e < 16; e += 2) {
;             f2_t pv; pv.x = __builtin_amdgcn_exp2f(S[t][e]); pv.y = __builtin_amdgcn_exp2f(S[t][e + 1]);
;             S[t][e] = pv.x; S[t][e + 1] = pv.y;
;             ps += pv;
;         }
;     lsum += ps.x + ps.y;
; }
; DI void pv_tile(const f32x16 (&S)[2], f32x16 (&O)[2], const bf16x8 (&vf)[8]) {
; #pragma unroll
;     for (int s = 0; s < 4; ++s) {
;         const bf16x8 pf = pack8(S[s >> 1], s & 1);
; #pragma unroll
;         for (int dt = 0; dt < 2; ++dt) O[dt] = MFMA(vf[2 * s + dt], pf, O[dt]);
;     }
; }
; template <int KIND>
; DI void attn_unit(const Params& p, int l, int b, int head, int qt, int qcol, int kcol, int vfeat, int gcol, int mixcol,
;                   int t1, int n1, int t2, int n2, char* smem) {
;     ...
;             if (KIND == 0) {
;                 f32x16 S0[2], S1[2];
; #pragma unroll
;                 for (int t = 0; t < 2; ++t) { S0[t] = MFMA(kf[t], qf[0], cz); S1[t] = MFMA(kf[4 + t], qf[2], cz); }
; #pragma unroll
;                 for (int t = 0; t < 2; ++t) { S0[t] = MFMA(kf[2 + t], qf[1], S0[t]); S1[t] = MFMA(kf[6 + t], qf[3], S1[t]); }
;                 LOAD_VF();
;                 softmax_tile(S0, l0);
;                 pv_tile(S0, O0, vf);
;                 softmax_tile(S1, l1);
;                 pv_tile(S1, O1, vf);
	v_mfma_f32_32x32x16_bf16 v[128:143], v[234:237], v[152:155], v[0:15]
	global_load_lds_dwordx4 v226, s[62:63]
	s_add_u32 m0, s101, 0x1000
	v_add_f32_e32 v252, v88, v252
	v_add_f32_e32 v253, v89, v253
	v_cvt_pk_bf16_f32 v88, v88, v89
	v_mfma_f32_32x32x16_bf16 v[112:127], v[238:241], v[152:155], v[0:15]
	global_load_lds_dwordx4 v227, s[62:63]
	s_add_u32 m0, s101, 0x2000
	v_add_f32_e32 v252, v90, v252
	v_add_f32_e32 v253, v91, v253
	v_cvt_pk_bf16_f32 v89, v90, v91
	v_mfma_f32_32x32x16_bf16 v[128:143], v[242:245], v[144:147], v[128:143]
	global_load_lds_dwordx4 v226, s[98:99]
	s_add_u32 m0, s101, 0x3000
	v_add_f32_e32 v252, v92, v252
	v_add_f32_e32 v253, v93, v253
	v_cvt_pk_bf16_f32 v90, v92, v93
	v_mfma_f32_32x32x16_bf16 v[112:127], v[246:249], v[144:147], v[112:127]
	global_load_lds_dwordx4 v227, s[98:99]
	v_add_f32_e32 v252, v94, v252
	v_add_f32_e32 v253, v95, v253
	v_cvt_pk_bf16_f32 v91, v94, v95
	v_add_f32_e32 v252, v252, v253
	v_add_f32_e32 v194, v194, v252
	s_cmp_lg_u32 s34, 2
	s_cselect_b32 s34, s42, 0
	s_add_u32 s62, s62, 0x2000
	s_addc_u32 s63, s63, 0
	s_add_u32 s98, s98, 0x2000
	s_addc_u32 s99, s99, 0
	ds_read_b128 v[234:237], v230
	ds_read_b128 v[238:241], v230 offset:4096
	ds_read_b128 v[242:245], v231
	ds_read_b128 v[246:249], v231 offset:4096
	v_mfma_f32_32x32x16_bf16 v[64:79], v[180:183], v[104:107], v[64:79]
	v_exp_f32_e32 v128, v128
	v_exp_f32_e32 v129, v129
	v_exp_f32_e32 v130, v130
	v_exp_f32_e32 v131, v131
	v_exp_f32_e32 v132, v132
	v_exp_f32_e32 v133, v133
	v_mfma_f32_32x32x16_bf16 v[16:31], v[176:179], v[104:107], v[16:31]
	v_exp_f32_e32 v134, v134
	v_exp_f32_e32 v135, v135
	v_exp_f32_e32 v136, v136
	v_exp_f32_e32 v137, v137
	v_exp_f32_e32 v138, v138
	v_exp_f32_e32 v139, v139
	v_add_f32_e64 v250, v128, 0
	v_add_f32_e64 v251, v129, 0
	v_cvt_pk_bf16_f32 v128, v128, v129
	v_add_f32_e32 v250, v130, v250
	v_add_f32_e32 v251, v131, v251
	v_cvt_pk_bf16_f32 v129, v130, v131
	v_add_f32_e32 v250, v132, v250
	v_add_f32_e32 v251, v133, v251
	v_cvt_pk_bf16_f32 v130, v132, v133
	v_mfma_f32_32x32x16_bf16 v[64:79], v[172:175], v[80:83], v[64:79]
	v_exp_f32_e32 v140, v140
	v_exp_f32_e32 v141, v141
	v_exp_f32_e32 v142, v142
	v_exp_f32_e32 v143, v143
	v_exp_f32_e32 v112, v112
	v_add_f32_e32 v250, v134, v250
	v_add_f32_e32 v251, v135, v251
	v_cvt_pk_bf16_f32 v131, v134, v135
	v_add_f32_e32 v250, v136, v250
	v_add_f32_e32 v251, v137, v251
	v_cvt_pk_bf16_f32 v136, v136, v137
	v_add_f32_e32 v250, v138, v250
	v_add_f32_e32 v251, v139, v251
	v_cvt_pk_bf16_f32 v137, v138, v139
	v_mfma_f32_32x32x16_bf16 v[16:31], v[168:171], v[80:83], v[16:31]
	v_exp_f32_e32 v113, v113
	v_exp_f32_e32 v114, v114
	v_exp_f32_e32 v115, v115
	v_exp_f32_e32 v116, v116
	v_exp_f32_e32 v117, v117
	v_add_f32_e32 v250, v140, v250
	v_add_f32_e32 v251, v141, v251
	v_cvt_pk_bf16_f32 v138, v140, v141
	v_add_f32_e32 v250, v142, v250
	v_add_f32_e32 v251, v143, v251
	v_cvt_pk_bf16_f32 v139, v142, v143
	v_mfma_f32_32x32x16_bf16 v[64:79], v[164:167], v[88:91], v[64:79]
	v_exp_f32_e32 v118, v118
	v_exp_f32_e32 v119, v119
	v_exp_f32_e32 v120, v120
	v_exp_f32_e32 v121, v121
	v_exp_f32_e32 v122, v122
	v_mfma_f32_32x32x16_bf16 v[16:31], v[160:163], v[88:91], v[16:31]
	v_exp_f32_e32 v123, v123
	v_exp_f32_e32 v124, v124
	v_exp_f32_e32 v125, v125
	v_exp_f32_e32 v126, v126
	v_exp_f32_e32 v127, v127
	s_waitcnt lgkmcnt(0)
; #define MFMA(a, b, c) __builtin_amdgcn_mfma_f32_32x32x16_bf16((a), (b), (c), 0, 0, 0)
; #define LOAD_VF() do { \
;             __builtin_amdgcn_sched_barrier(0); \
;             _Pragma("unroll") for (int s = 0; s < 4; ++s) \
;                 _Pragma("unroll") for (int dt = 0; dt < 2; ++dt) vf[2 * s + dt] = ldv_frag(sv, 32 * dt + r, 2 * s + h, xr); \
;             __builtin_amdgcn_sched_barrier(0); } while (0)
; DI void softmax_tile(f32x16 (&S)[2], float& lsum) {
;     f2_t ps = {0.f, 0.f};
; #pragma unroll
;     for (int t = 0; t < 2; ++t)
; #pragma unroll
;         for (int e = 0; e < 16; e += 2) {
;             f2_t pv; pv.x = __builtin_amdgcn_exp2f(S[t][e]); pv.y = __builtin_amdgcn_exp2f(S[t][e + 1]);
;             S[t][e] = pv.x; S[t][e + 1] = pv.y;
;             ps += pv;
;         }
;     lsum += ps.x + ps.y;
; }
; DI void pv_tile(const f32x16 (&S)[2], f32x16 (&O)[2], const bf16x8 (&vf)[8]) {
; #pragma unroll
;     for (int s = 0; s < 4; ++s) {
;         const bf16x8 pf = pack8(S[s >> 1], s & 1);
; #pragma unroll
;         for (int dt = 0; dt < 2; ++dt) O[dt] = MFMA(vf[2 * s + dt], pf, O[dt]);
;     }
; }
; template <int KIND>
; DI void attn_unit(const Params& p, int l, int b, int head, int qt, int qcol, int kcol, int vfeat, int gcol, int mixcol,
;                   int t1, int n1, int t2, int n2, char* smem) {
;     ...
;             if (KIND == 0) {
;                 f32x16 S0[2], S1[2];
; #pragma unroll
;                 for (int t = 0; t < 2; ++t) { S0[t] = MFMA(kf[t], qf[0], cz); S1[t] = MFMA(kf[4 + t], qf[2], cz); }
; #pragma unroll
;                 for (int t = 0; t < 2; ++t) { S0[t] = MFMA(kf[2 + t], qf[1], S0[t]); S1[t] = MFMA(kf[6 + t], qf[3], S1[t]); }
;                 LOAD_VF();
;                 softmax_tile(S0, l0);
;                 pv_tile(S0, O0, vf);
;                 softmax_tile(S1, l1);
;                 pv_tile(S1, O1, vf);
	ds_read_b128 v[188:191], v228 offset:8192
	ds_read_b128 v[184:187], v228 offset:12288
	ds_read_b128 v[180:183], v229 offset:8192
	ds_read_b128 v[176:179], v229 offset:12288
	ds_read_b128 v[172:175], v230 offset:8192
	ds_read_b128 v[168:171], v230 offset:12288
	ds_read_b128 v[164:167], v231 offset:8192
	ds_read_b128 v[160:163], v231 offset:12288
	v_mfma_f32_32x32x16_bf16 v[96:111], v[234:237], v[156:159], v[0:15]
	v_add_f32_e32 v250, v112, v250
	v_add_f32_e32 v251, v113, v251
	v_cvt_pk_bf16_f32 v112, v112, v113
	v_add_f32_e32 v250, v114, v250
	v_add_f32_e32 v251, v115, v251
	v_cvt_pk_bf16_f32 v113, v114, v115
	v_mfma_f32_32x32x16_bf16 v[80:95], v[238:241], v[156:159], v[0:15]
	v_add_f32_e32 v250, v116, v250
	v_add_f32_e32 v251, v117, v251
	v_cvt_pk_bf16_f32 v114, v116, v117
	v_add_f32_e32 v250, v118, v250
	v_add_f32_e32 v251, v119, v251
	v_cvt_pk_bf16_f32 v115, v118, v119
	v_mfma_f32_32x32x16_bf16 v[96:111], v[242:245], v[148:151], v[96:111]
	v_add_f32_e32 v250, v120, v250
	v_add_f32_e32 v251, v121, v251
	v_cvt_pk_bf16_f32 v120, v120, v121
	v_add_f32_e32 v250, v122, v250
	v_add_f32_e32 v251, v123, v251
	v_cvt_pk_bf16_f32 v121, v122, v123
	v_mfma_f32_32x32x16_bf16 v[80:95], v[246:249], v[148:151], v[80:95]
	v_add_f32_e32 v250, v124, v250
	v_add_f32_e32 v251, v125, v251
	v_cvt_pk_bf16_f32 v122, v124, v125
	v_add_f32_e32 v250, v126, v250
	v_add_f32_e32 v251, v127, v251
	v_cvt_pk_bf16_f32 v123, v126, v127
	v_add_f32_e32 v250, v250, v251
	v_add_f32_e32 v195, v195, v250
	s_add_u32 s4, s4, 0x2000
	s_addc_u32 s5, s5, 0
	s_waitcnt lgkmcnt(0)
	v_mfma_f32_32x32x16_bf16 v[48:63], v[188:191], v[128:131], v[48:63]
	v_exp_f32_e32 v96, v96
	v_exp_f32_e32 v97, v97
	v_exp_f32_e32 v98, v98
	v_exp_f32_e32 v99, v99
	v_mfma_f32_32x32x16_bf16 v[32:47], v[184:187], v[128:131], v[32:47]
	v_exp_f32_e32 v100, v100
	v_exp_f32_e32 v101, v101
	v_exp_f32_e32 v102, v102
	v_exp_f32_e32 v103, v103
	v_mfma_f32_32x32x16_bf16 v[48:63], v[180:183], v[136:139], v[48:63]
	v_exp_f32_e32 v104, v104
	v_exp_f32_e32 v105, v105
	v_exp_f32_e32 v106, v106
	v_exp_f32_e32 v107, v107
	v_add_f32_e64 v252, v96, 0
	v_add_f32_e64 v253, v97, 0
	v_cvt_pk_bf16_f32 v96, v96, v97
	v_add_f32_e32 v252, v98, v252
	v_add_f32_e32 v253, v99, v253
	v_cvt_pk_bf16_f32 v97, v98, v99
	v_mfma_f32_32x32x16_bf16 v[32:47], v[176:179], v[136:139], v[32:47]
	v_exp_f32_e32 v108, v108
	v_exp_f32_e32 v109, v109
	v_exp_f32_e32 v110, v110
	v_exp_f32_e32 v111, v111
	v_add_f32_e32 v252, v100, v252
	v_add_f32_e32 v253, v101, v253
	v_cvt_pk_bf16_f32 v98, v100, v101
	v_add_f32_e32 v252, v102, v252
	v_add_f32_e32 v253, v103, v253
	v_cvt_pk_bf16_f32 v99, v102, v103
	v_mfma_f32_32x32x16_bf16 v[48:63], v[172:175], v[112:115], v[48:63]
	v_exp_f32_e32 v80, v80
	v_exp_f32_e32 v81, v81
	v_exp_f32_e32 v82, v82
	v_exp_f32_e32 v83, v83
	v_add_f32_e32 v252, v104, v252
	v_add_f32_e32 v253, v105, v253
	v_cvt_pk_bf16_f32 v104, v104, v105
	v_add_f32_e32 v252, v106, v252
	v_add_f32_e32 v253, v107, v253
	v_cvt_pk_bf16_f32 v105, v106, v107
	v_mfma_f32_32x32x16_bf16 v[32:47], v[168:171], v[112:115], v[32:47]
	v_exp_f32_e32 v84, v84
	v_exp_f32_e32 v85, v85
	v_exp_f32_e32 v86, v86
	v_exp_f32_e32 v87, v87
	v_add_f32_e32 v252, v108, v252
	v_add_f32_e32 v253, v109, v253
	v_cvt_pk_bf16_f32 v106, v108, v109
	v_add_f32_e32 v252, v110, v252
	v_add_f32_e32 v253, v111, v253
	v_cvt_pk_bf16_f32 v107, v110, v111
	v_mfma_f32_32x32x16_bf16 v[48:63], v[164:167], v[120:123], v[48:63]
	v_exp_f32_e32 v88, v88
	v_exp_f32_e32 v89, v89
	v_exp_f32_e32 v90, v90
	v_exp_f32_e32 v91, v91
	v_mfma_f32_32x32x16_bf16 v[32:47], v[160:163], v[120:123], v[32:47]
	v_exp_f32_e32 v92, v92
	v_exp_f32_e32 v93, v93
	v_exp_f32_e32 v94, v94
	v_exp_f32_e32 v95, v95
	s_cmp_eq_u32 s52, s4
	s_cbranch_scc0 .LBB0_82
